# adds: mixer C direct branch targets (no double tests), residual GEMM epilogue software-pipelined with 2 atomics per tile, code placement kept equal to previous best via cold-spot padding
# baseline (speedup 1.0000x reference)
; #define LAS __attribute__((address_space(3)))
;     __device__ __forceinline__ void apply(f32x16& p0, f32x16& p1, int, int) const {
;         if (inb) {
; #pragma unroll
;             for (int r = 0; r < 16; ++r) { const float cr = (float)((r & 3) + 8 * (r >> 2));
;                 { const float d = __builtin_fmaf(-cr, strf, af); const float v = __builtin_fmaf(-slope2, __builtin_fabsf(d), p0[r]); p0[r] = (__builtin_fabsf(d) <= limf) ? v : -INFINITY; }
;                 { const float d = __builtin_fmaf(-(cr + 32.f), strf, af); const float v = __builtin_fmaf(-slope2, __builtin_fabsf(d), p1[r]); p1[r] = (__builtin_fabsf(d) <= limf) ? v : -INFINITY; } }
; __device__ __forceinline__ void qkt2(f32x16& p0, f32x16& p1, LAS const unsigned char* kslot, const bf16x8 (&qr)[4], const f32x16& negm, int r32, int hi) {
; #pragma unroll
;     for (int d0 = 0; d0 < 4; ++d0) {
;         LAS const unsigned char* kb = kslot + (2 * d0 + hi) * 1024 + ((r32 ^ (2 * d0 + hi)) * 16); asm volatile("" : "+v"(kb));
;         const bf16x8 b0 = *(LAS const bf16x8*)(kb);
;         const bf16x8 b1 = *(LAS const bf16x8*)(kb + 512);
;         if (d0 == 0) { p0 = __builtin_amdgcn_mfma_f32_32x32x16_bf16(b0, qr[0], negm, 0, 0, 0); p1 = __builtin_amdgcn_mfma_f32_32x32x16_bf16(b1, qr[0], negm, 0, 0, 0); }
;         else { p0 = __builtin_amdgcn_mfma_f32_32x32x16_bf16(b0, qr[d0], p0, 0, 0, 0); p1 = __builtin_amdgcn_mfma_f32_32x32x16_bf16(b1, qr[d0], p1, 0, 0, 0); }
;     }
; }
.Lk39:
	v_add_u32_e32 v50, s16, v50
	v_mad_i64_i32 v[50:51], s[2:3], v50, s98, v[172:173]
	s_lshl_b32 s10, 0x6200, s41
	s_lshl_b32 s54, s10, 1
	s_lshl_b32 s2, 0xc400, s41
	v_lshl_add_u64 v[52:53], v[50:51], 0, s[54:55]
	s_lshl_b32 s54, s2, 1
	s_lshl_b32 s2, 0x18800, s41
	global_load_dwordx4 v[98:101], v[50:51], off offset:2048
	global_load_dwordx4 v[102:105], v[52:53], off offset:2048
	v_lshl_add_u64 v[52:53], v[50:51], 0, s[54:55]
	s_mul_i32 s54, s10, 6
	s_lshl_b32 s2, s2, 1
	s_mov_b32 s3, s55
	v_lshl_add_u64 v[54:55], v[50:51], 0, s[54:55]
	global_load_dwordx4 v[106:109], v[52:53], off offset:2048
	global_load_dwordx4 v[110:113], v[54:55], off offset:2048
	v_lshl_add_u64 v[52:53], v[50:51], 0, s[2:3]
	s_mul_i32 s2, s10, 10
	s_lshl_b32 s54, s54, 1
	v_lshl_add_u64 v[54:55], v[50:51], 0, s[2:3]
	global_load_dwordx4 v[114:117], v[52:53], off offset:2048
	global_load_dwordx4 v[118:121], v[54:55], off offset:2048
	v_lshl_add_u64 v[52:53], v[50:51], 0, s[54:55]
	s_mul_i32 s54, s10, 14
	v_lshl_add_u64 v[50:51], v[50:51], 0, s[54:55]
	global_load_dwordx4 v[122:125], v[52:53], off offset:2048
	global_load_dwordx4 v[126:129], v[50:51], off offset:2048
.LBB0_40:
	v_lshlrev_b32_e32 v50, s43, v236
	v_subrev_u32_e32 v50, s42, v50
	v_add_u32_e32 v50, v50, v188
	v_cvt_f32_i32_e32 v218, v50
	v_mov_b32_e32 v50, v237
	ds_read_b128 v[176:179], v50 offset:512
	ds_read_b128 v[66:69], v50
	v_mov_b32_e32 v169, v238
	s_lshl_b32 s2, 1, s43
	s_waitcnt lgkmcnt(0)
	v_mfma_f32_32x32x16_bf16 v[50:65], v[66:69], v[82:85], v[34:49]
	v_cvt_f32_u32_e32 v220, s2
	s_lshl_b32 s2, 64, s43
	v_mfma_f32_32x32x16_bf16 v[66:81], v[176:179], v[82:85], v[34:49]
	ds_read_b128 v[176:179], v169 offset:512
	ds_read_b128 v[180:183], v169
	v_mov_b32_e32 v169, v239
	s_cmp_gt_i32 s42, -1
	v_cvt_f32_u32_e32 v171, s2
	s_cselect_b64 s[2:3], -1, 0
	s_lshl_b32 s10, 63, s43
	s_waitcnt lgkmcnt(0)
	v_mfma_f32_32x32x16_bf16 v[50:65], v[180:183], v[86:89], v[50:65]
	s_add_i32 s10, s42, s10
	s_cmp_lt_i32 s10, s23
	s_cselect_b64 s[10:11], -1, 0
	s_and_b64 s[10:11], s[2:3], s[10:11]
	v_sub_f32_e32 v248, v218, v220
	v_cmp_le_f32_e64 s[42:43], |v218|, v171
	v_mfma_f32_32x32x16_bf16 v[66:81], v[176:179], v[86:89], v[66:81]
	ds_read_b128 v[176:179], v169 offset:512
	ds_read_b128 v[180:183], v169
	v_mov_b32_e32 v169, v240
	s_and_b64 vcc, exec, s[10:11]
	v_cmp_le_f32_e64 s[10:11], |v248|, v171
	v_fma_f32 v249, -2.0, v220, v218
	v_fmamk_f32 v247, v220, 0xc2680000, v218
	s_waitcnt lgkmcnt(0)
	v_mfma_f32_32x32x16_bf16 v[50:65], v[180:183], v[90:93], v[50:65]
	v_fmamk_f32 v246, v220, 0xc1d80000, v218
	v_fmamk_f32 v245, v220, 0xc26c0000, v218
	v_mfma_f32_32x32x16_bf16 v[66:81], v[176:179], v[90:93], v[66:81]
	ds_read_b128 v[176:179], v169 offset:512
	ds_read_b128 v[180:183], v169
	s_waitcnt lgkmcnt(0)
	v_mfma_f32_32x32x16_bf16 v[50:65], v[180:183], v[94:97], v[50:65]
	v_mfma_f32_32x32x16_bf16 v[66:81], v[176:179], v[94:97], v[66:81]
	s_nop 10
	v_fma_f32 v250, v186, |v218|, v50
	s_cbranch_vccnz .Linb43
	v_cvt_f32_i32_e32 v176, v188
	v_subrev_u32_e32 v50, s23, v188
	v_cvt_f32_i32_e32 v177, v50
	v_fmamk_f32 v50, v220, 0xc2000000, v218
	v_cmp_le_f32_e32 vcc, v218, v176
	s_and_b64 s[2:3], s[42:43], vcc
	v_cmp_gt_f32_e32 vcc, v218, v177
	s_and_b64 vcc, s[2:3], vcc
	v_cmp_le_f32_e64 s[2:3], |v50|, v171
	v_cndmask_b32_e32 v188, v226, v250, vcc
	v_cmp_le_f32_e32 vcc, v50, v176
	s_and_b64 s[2:3], s[2:3], vcc
	v_cmp_gt_f32_e32 vcc, v50, v177
	v_fma_f32 v169, v186, |v50|, v66
	s_and_b64 vcc, s[2:3], vcc
	v_cndmask_b32_e32 v50, v226, v169, vcc
	v_cmp_le_f32_e32 vcc, v248, v176
	s_and_b64 s[2:3], s[10:11], vcc
	v_cmp_gt_f32_e32 vcc, v248, v177
	v_fma_f32 v169, v186, |v248|, v51
	s_and_b64 vcc, s[2:3], vcc
	v_cndmask_b32_e32 v189, v226, v169, vcc
	v_fmamk_f32 v169, v220, 0xc2040000, v218
	v_cmp_le_f32_e64 s[2:3], |v169|, v171
	v_cmp_le_f32_e32 vcc, v169, v176
	s_and_b64 s[2:3], s[2:3], vcc
	v_cmp_gt_f32_e32 vcc, v169, v177
	v_fma_f32 v178, v186, |v169|, v67
	s_and_b64 vcc, s[2:3], vcc
	v_cndmask_b32_e32 v169, v226, v178, vcc
	v_cmp_le_f32_e64 s[2:3], |v249|, v171
	v_cmp_le_f32_e32 vcc, v249, v176
	s_and_b64 s[2:3], s[2:3], vcc
	v_cmp_gt_f32_e32 vcc, v249, v177
	v_fma_f32 v178, v186, |v249|, v52
	s_and_b64 vcc, s[2:3], vcc
	v_cndmask_b32_e32 v190, v226, v178, vcc
	v_fmamk_f32 v178, v220, 0xc2080000, v218
	v_cmp_le_f32_e64 s[2:3], |v178|, v171
	v_cmp_le_f32_e32 vcc, v178, v176
	s_and_b64 s[2:3], s[2:3], vcc
	v_cmp_gt_f32_e32 vcc, v178, v177
	v_fma_f32 v179, v186, |v178|, v68
	s_and_b64 vcc, s[2:3], vcc
	v_fmamk_f32 v178, v220, 0xc0400000, v218
	v_cndmask_b32_e32 v194, v226, v179, vcc
	v_cmp_le_f32_e64 s[2:3], |v178|, v171
	v_cmp_le_f32_e32 vcc, v178, v176
	s_and_b64 s[2:3], s[2:3], vcc
	v_cmp_gt_f32_e32 vcc, v178, v177
	v_fma_f32 v179, v186, |v178|, v53
	s_and_b64 vcc, s[2:3], vcc
	v_fmamk_f32 v178, v220, 0xc20c0000, v218
	v_cndmask_b32_e32 v191, v226, v179, vcc
	v_cmp_le_f32_e64 s[2:3], |v178|, v171
	v_cmp_le_f32_e32 vcc, v178, v176
	s_and_b64 s[2:3], s[2:3], vcc
	v_cmp_gt_f32_e32 vcc, v178, v177
	v_fma_f32 v179, v186, |v178|, v69
	s_and_b64 vcc, s[2:3], vcc
	v_fmamk_f32 v178, v220, 0xc1000000, v218
	v_cndmask_b32_e32 v195, v226, v179, vcc
	v_cmp_le_f32_e64 s[2:3], |v178|, v171
	v_cmp_le_f32_e32 vcc, v178, v176
	s_and_b64 s[2:3], s[2:3], vcc
	v_cmp_gt_f32_e32 vcc, v178, v177
	v_fma_f32 v179, v186, |v178|, v54
	s_and_b64 vcc, s[2:3], vcc
	v_fmamk_f32 v178, v220, 0xc2200000, v218
	v_cndmask_b32_e32 v192, v226, v179, vcc
	v_cmp_le_f32_e64 s[2:3], |v178|, v171
	v_cmp_le_f32_e32 vcc, v178, v176
	s_and_b64 s[2:3], s[2:3], vcc
	v_cmp_gt_f32_e32 vcc, v178, v177
	v_fma_f32 v179, v186, |v178|, v70
	s_and_b64 vcc, s[2:3], vcc
;     __device__ __forceinline__ void apply(f32x16& p0, f32x16& p1, int, int) const {
;     ...
;             for (int r = 0; r < 16; ++r) { const float cr = (float)((r & 3) + 8 * (r >> 2));
;                 { const float d = __builtin_fmaf(-cr, strf, af); const float v = __builtin_fmaf(-slope2, __builtin_fabsf(d), p0[r]); p0[r] = ((__builtin_fabsf(d) <= limf) && (d <= tqf) && (d > tqmS)) ? v : -INFINITY; }
;                 { const float d = __builtin_fmaf(-(cr + 32.f), strf, af); const float v = __builtin_fmaf(-slope2, __builtin_fabsf(d), p1[r]); p1[r] = ((__builtin_fabsf(d) <= limf) && (d <= tqf) && (d > tqmS)) ? v : -INFINITY; } }
	v_fmamk_f32 v178, v220, 0xc1100000, v218
	v_cndmask_b32_e32 v196, v226, v179, vcc
	v_cmp_le_f32_e64 s[2:3], |v178|, v171
	v_cmp_le_f32_e32 vcc, v178, v176
	s_and_b64 s[2:3], s[2:3], vcc
	v_cmp_gt_f32_e32 vcc, v178, v177
	v_fma_f32 v179, v186, |v178|, v55
	s_and_b64 vcc, s[2:3], vcc
	v_fmamk_f32 v178, v220, 0xc2240000, v218
	v_cndmask_b32_e32 v193, v226, v179, vcc
	v_cmp_le_f32_e64 s[2:3], |v178|, v171
	v_cmp_le_f32_e32 vcc, v178, v176
	s_and_b64 s[2:3], s[2:3], vcc
	v_cmp_gt_f32_e32 vcc, v178, v177
	v_fma_f32 v179, v186, |v178|, v71
	s_and_b64 vcc, s[2:3], vcc
	v_fmamk_f32 v178, v220, 0xc1200000, v218
	v_cndmask_b32_e32 v197, v226, v179, vcc
	v_cmp_le_f32_e64 s[2:3], |v178|, v171
	v_cmp_le_f32_e32 vcc, v178, v176
	s_and_b64 s[2:3], s[2:3], vcc
	v_cmp_gt_f32_e32 vcc, v178, v177
	v_fma_f32 v179, v186, |v178|, v56
	s_and_b64 vcc, s[2:3], vcc
	v_fmamk_f32 v178, v220, 0xc2280000, v218
	v_cndmask_b32_e32 v198, v226, v179, vcc
	v_cmp_le_f32_e64 s[2:3], |v178|, v171
	v_cmp_le_f32_e32 vcc, v178, v176
	s_and_b64 s[2:3], s[2:3], vcc
	v_cmp_gt_f32_e32 vcc, v178, v177
	v_fma_f32 v179, v186, |v178|, v72
	s_and_b64 vcc, s[2:3], vcc
	v_fmamk_f32 v178, v220, 0xc1300000, v218
	v_cndmask_b32_e32 v200, v226, v179, vcc
	v_cmp_le_f32_e64 s[2:3], |v178|, v171
	v_cmp_le_f32_e32 vcc, v178, v176
	s_and_b64 s[2:3], s[2:3], vcc
	v_cmp_gt_f32_e32 vcc, v178, v177
	v_fma_f32 v179, v186, |v178|, v57
	s_and_b64 vcc, s[2:3], vcc
	v_fmamk_f32 v178, v220, 0xc22c0000, v218
	v_cndmask_b32_e32 v199, v226, v179, vcc
	v_cmp_le_f32_e64 s[2:3], |v178|, v171
	v_cmp_le_f32_e32 vcc, v178, v176
	s_and_b64 s[2:3], s[2:3], vcc
	v_cmp_gt_f32_e32 vcc, v178, v177
	v_fma_f32 v179, v186, |v178|, v73
	s_and_b64 vcc, s[2:3], vcc
	v_fmamk_f32 v178, v220, 0xc1800000, v218
	v_cndmask_b32_e32 v201, v226, v179, vcc
	v_cmp_le_f32_e64 s[2:3], |v178|, v171
	v_cmp_le_f32_e32 vcc, v178, v176
	s_and_b64 s[2:3], s[2:3], vcc
	v_cmp_gt_f32_e32 vcc, v178, v177
	v_fma_f32 v179, v186, |v178|, v58
	s_and_b64 vcc, s[2:3], vcc
	v_fmamk_f32 v178, v220, 0xc2400000, v218
	v_cndmask_b32_e32 v202, v226, v179, vcc
	v_cmp_le_f32_e64 s[2:3], |v178|, v171
	v_cmp_le_f32_e32 vcc, v178, v176
	s_and_b64 s[2:3], s[2:3], vcc
	v_cmp_gt_f32_e32 vcc, v178, v177
	v_fma_f32 v179, v186, |v178|, v74
	s_and_b64 vcc, s[2:3], vcc
	v_fmamk_f32 v178, v220, 0xc1880000, v218
	v_cndmask_b32_e32 v204, v226, v179, vcc
	v_cmp_le_f32_e64 s[2:3], |v178|, v171
	v_cmp_le_f32_e32 vcc, v178, v176
	s_and_b64 s[2:3], s[2:3], vcc
	v_cmp_gt_f32_e32 vcc, v178, v177
	v_fma_f32 v179, v186, |v178|, v59
	s_and_b64 vcc, s[2:3], vcc
	v_fmamk_f32 v178, v220, 0xc2440000, v218
	v_cndmask_b32_e32 v203, v226, v179, vcc
	v_cmp_le_f32_e64 s[2:3], |v178|, v171
	v_cmp_le_f32_e32 vcc, v178, v176
	s_and_b64 s[2:3], s[2:3], vcc
	v_cmp_gt_f32_e32 vcc, v178, v177
	v_fma_f32 v179, v186, |v178|, v75
	s_and_b64 vcc, s[2:3], vcc
	v_fmamk_f32 v178, v220, 0xc1900000, v218
	v_cndmask_b32_e32 v205, v226, v179, vcc
	v_cmp_le_f32_e64 s[2:3], |v178|, v171
	v_cmp_le_f32_e32 vcc, v178, v176
	s_and_b64 s[2:3], s[2:3], vcc
	v_cmp_gt_f32_e32 vcc, v178, v177
	v_fma_f32 v179, v186, |v178|, v60
	s_and_b64 vcc, s[2:3], vcc
	v_fmamk_f32 v178, v220, 0xc2480000, v218
	v_cndmask_b32_e32 v206, v226, v179, vcc
	v_cmp_le_f32_e64 s[2:3], |v178|, v171
	v_cmp_le_f32_e32 vcc, v178, v176
	s_and_b64 s[2:3], s[2:3], vcc
	v_cmp_gt_f32_e32 vcc, v178, v177
	v_fma_f32 v179, v186, |v178|, v76
	s_and_b64 vcc, s[2:3], vcc
	v_fmamk_f32 v178, v220, 0xc1980000, v218
	v_cndmask_b32_e32 v208, v226, v179, vcc
	v_cmp_le_f32_e64 s[2:3], |v178|, v171
	v_cmp_le_f32_e32 vcc, v178, v176
	s_and_b64 s[2:3], s[2:3], vcc
	v_cmp_gt_f32_e32 vcc, v178, v177
	v_fma_f32 v179, v186, |v178|, v61
	s_and_b64 vcc, s[2:3], vcc
	v_fmamk_f32 v178, v220, 0xc24c0000, v218
	v_cndmask_b32_e32 v207, v226, v179, vcc
	v_cmp_le_f32_e64 s[2:3], |v178|, v171
	v_cmp_le_f32_e32 vcc, v178, v176
	s_and_b64 s[2:3], s[2:3], vcc
	v_cmp_gt_f32_e32 vcc, v178, v177
	v_fma_f32 v179, v186, |v178|, v77
	s_and_b64 vcc, s[2:3], vcc
	v_fmamk_f32 v178, v220, 0xc1c00000, v218
	v_cndmask_b32_e32 v209, v226, v179, vcc
	v_cmp_le_f32_e64 s[2:3], |v178|, v171
	v_cmp_le_f32_e32 vcc, v178, v176
	s_and_b64 s[2:3], s[2:3], vcc
	v_cmp_gt_f32_e32 vcc, v178, v177
	v_fma_f32 v179, v186, |v178|, v62
	s_and_b64 vcc, s[2:3], vcc
	v_fmamk_f32 v178, v220, 0xc2600000, v218
	v_cndmask_b32_e32 v210, v226, v179, vcc
	v_cmp_le_f32_e64 s[2:3], |v178|, v171
	v_cmp_le_f32_e32 vcc, v178, v176
	s_and_b64 s[2:3], s[2:3], vcc
	v_cmp_gt_f32_e32 vcc, v178, v177
	v_fma_f32 v179, v186, |v178|, v78
	s_and_b64 vcc, s[2:3], vcc
	v_fmamk_f32 v178, v220, 0xc1c80000, v218
	v_cndmask_b32_e32 v212, v226, v179, vcc
	v_cmp_le_f32_e64 s[2:3], |v178|, v171
	v_cmp_le_f32_e32 vcc, v178, v176
	s_and_b64 s[2:3], s[2:3], vcc
	v_cmp_gt_f32_e32 vcc, v178, v177
	v_fma_f32 v179, v186, |v178|, v63
	s_and_b64 vcc, s[2:3], vcc
	v_fmamk_f32 v178, v220, 0xc2640000, v218
	v_cndmask_b32_e32 v211, v226, v179, vcc
	v_cmp_le_f32_e64 s[2:3], |v178|, v171
	v_cmp_le_f32_e32 vcc, v178, v176
	s_and_b64 s[2:3], s[2:3], vcc
	v_cmp_gt_f32_e32 vcc, v178, v177
	v_fma_f32 v179, v186, |v178|, v79
	s_and_b64 vcc, s[2:3], vcc
	v_fmamk_f32 v178, v220, 0xc1d00000, v218
	v_cndmask_b32_e32 v213, v226, v179, vcc
	v_cmp_le_f32_e64 s[2:3], |v178|, v171
	v_cmp_le_f32_e32 vcc, v178, v176
	s_and_b64 s[2:3], s[2:3], vcc
	v_cmp_gt_f32_e32 vcc, v178, v177
	v_fma_f32 v179, v186, |v178|, v64
	s_and_b64 vcc, s[2:3], vcc
	v_cndmask_b32_e32 v214, v226, v179, vcc
	v_cmp_le_f32_e64 s[2:3], |v247|, v171
	v_cmp_le_f32_e32 vcc, v247, v176
	s_and_b64 s[2:3], s[2:3], vcc
	v_cmp_gt_f32_e32 vcc, v247, v177
	v_fma_f32 v178, v186, |v247|, v80
	s_and_b64 vcc, s[2:3], vcc
	v_cndmask_b32_e32 v216, v226, v178, vcc
	v_cmp_le_f32_e64 s[2:3], |v246|, v171
	v_cmp_le_f32_e32 vcc, v246, v176
	s_and_b64 s[2:3], s[2:3], vcc
	v_cmp_gt_f32_e32 vcc, v246, v177
	v_fma_f32 v178, v186, |v246|, v65
	s_and_b64 vcc, s[2:3], vcc
	v_cndmask_b32_e32 v215, v226, v178, vcc
	v_cmp_le_f32_e64 s[2:3], |v245|, v171
	v_cmp_le_f32_e32 vcc, v245, v176
	s_and_b64 s[2:3], s[2:3], vcc
	v_cmp_gt_f32_e32 vcc, v245, v177
	v_fma_f32 v178, v186, |v245|, v81
	s_and_b64 vcc, s[2:3], vcc
	v_cndmask_b32_e32 v217, v226, v178, vcc
	s_mov_b64 s[2:3], 0

;     __device__ __forceinline__ void apply(f32x16& p0, f32x16& p1, int, int) const {
;         if (inb) {
; #pragma unroll
;             for (int r = 0; r < 16; ++r) { const float cr = (float)((r & 3) + 8 * (r >> 2));
;                 { const float d = __builtin_fmaf(-cr, strf, af); const float v = __builtin_fmaf(-slope2, __builtin_fabsf(d), p0[r]); p0[r] = (__builtin_fabsf(d) <= limf) ? v : -INFINITY; }
;                 { const float d = __builtin_fmaf(-(cr + 32.f), strf, af); const float v = __builtin_fmaf(-slope2, __builtin_fabsf(d), p1[r]); p1[r] = (__builtin_fabsf(d) <= limf) ? v : -INFINITY; } }
.Linb43:
	v_fma_f32 v179, s62, v220, v218
	v_fma_f32 v189, v186, |v248|, v51
	v_fma_f32 v190, v186, |v249|, v52
	v_fma_f32 v191, v186, |v179|, v53
	v_cmp_le_f32_e64 vcc, |v249|, v171
	v_cmp_le_f32_e64 s[2:3], |v179|, v171
	v_cndmask_b32_e64 v188, v226, v250, s[42:43]
	v_cndmask_b32_e64 v189, v226, v189, s[10:11]
	v_cndmask_b32_e32 v190, v226, v190, vcc
	v_cndmask_b32_e64 v191, v226, v191, s[2:3]
	v_fma_f32 v176, s63, v220, v218
	v_fma_f32 v177, s66, v220, v218
	v_fma_f32 v178, s67, v220, v218
	v_fma_f32 v179, s70, v220, v218
	v_fma_f32 v192, v186, |v176|, v54
	v_fma_f32 v193, v186, |v177|, v55
	v_fma_f32 v198, v186, |v178|, v56
	v_fma_f32 v199, v186, |v179|, v57
	v_cmp_le_f32_e64 vcc, |v176|, v171
	v_cmp_le_f32_e64 s[2:3], |v177|, v171
	v_cmp_le_f32_e64 s[10:11], |v178|, v171
	v_cmp_le_f32_e64 s[42:43], |v179|, v171
	v_cndmask_b32_e32 v192, v226, v192, vcc
	v_cndmask_b32_e64 v193, v226, v193, s[2:3]
	v_cndmask_b32_e64 v198, v226, v198, s[10:11]
	v_cndmask_b32_e64 v199, v226, v199, s[42:43]
	v_fma_f32 v176, s71, v220, v218
	v_fma_f32 v177, s74, v220, v218
	v_fma_f32 v178, s75, v220, v218
	v_fma_f32 v179, s78, v220, v218
	v_fma_f32 v202, v186, |v176|, v58
	v_fma_f32 v203, v186, |v177|, v59
	v_fma_f32 v206, v186, |v178|, v60
	v_fma_f32 v207, v186, |v179|, v61
	v_cmp_le_f32_e64 vcc, |v176|, v171
	v_cmp_le_f32_e64 s[2:3], |v177|, v171
	v_cmp_le_f32_e64 s[10:11], |v178|, v171
	v_cmp_le_f32_e64 s[42:43], |v179|, v171
	v_cndmask_b32_e32 v202, v226, v202, vcc
	v_cndmask_b32_e64 v203, v226, v203, s[2:3]
	v_cndmask_b32_e64 v206, v226, v206, s[10:11]
	v_cndmask_b32_e64 v207, v226, v207, s[42:43]
	v_fma_f32 v176, s79, v220, v218
	v_fma_f32 v177, s82, v220, v218
	v_fma_f32 v178, s83, v220, v218
	v_fma_f32 v210, v186, |v176|, v62
	v_fma_f32 v211, v186, |v177|, v63
	v_fma_f32 v214, v186, |v178|, v64
	v_fma_f32 v215, v186, |v246|, v65
	v_cmp_le_f32_e64 vcc, |v176|, v171
	v_cmp_le_f32_e64 s[2:3], |v177|, v171
	v_cmp_le_f32_e64 s[10:11], |v178|, v171
	v_cmp_le_f32_e64 s[42:43], |v246|, v171
	v_cndmask_b32_e32 v210, v226, v210, vcc
	v_cndmask_b32_e64 v211, v226, v211, s[2:3]
	v_cndmask_b32_e64 v214, v226, v214, s[10:11]
	v_cndmask_b32_e64 v215, v226, v215, s[42:43]
	v_fma_f32 v176, s58, v220, v218
	v_fma_f32 v177, s59, v220, v218
	v_fma_f32 v178, s60, v220, v218
	v_fma_f32 v179, s61, v220, v218
	v_fma_f32 v50, v186, |v176|, v66
	v_fma_f32 v169, v186, |v177|, v67
	v_fma_f32 v194, v186, |v178|, v68
	v_fma_f32 v195, v186, |v179|, v69
	v_cmp_le_f32_e64 vcc, |v176|, v171
	v_cmp_le_f32_e64 s[2:3], |v177|, v171
	v_cmp_le_f32_e64 s[10:11], |v178|, v171
	v_cmp_le_f32_e64 s[42:43], |v179|, v171
	v_cndmask_b32_e32 v50, v226, v50, vcc
	v_cndmask_b32_e64 v169, v226, v169, s[2:3]
	v_cndmask_b32_e64 v194, v226, v194, s[10:11]
	v_cndmask_b32_e64 v195, v226, v195, s[42:43]
	v_fma_f32 v176, s64, v220, v218
	v_fma_f32 v177, s65, v220, v218
	v_fma_f32 v178, s68, v220, v218
	v_fma_f32 v179, s69, v220, v218
	v_fma_f32 v196, v186, |v176|, v70
	v_fma_f32 v197, v186, |v177|, v71
	v_fma_f32 v200, v186, |v178|, v72
	v_fma_f32 v201, v186, |v179|, v73
	v_cmp_le_f32_e64 vcc, |v176|, v171
	v_cmp_le_f32_e64 s[2:3], |v177|, v171
	v_cmp_le_f32_e64 s[10:11], |v178|, v171
	v_cmp_le_f32_e64 s[42:43], |v179|, v171
	v_cndmask_b32_e32 v196, v226, v196, vcc
	v_cndmask_b32_e64 v197, v226, v197, s[2:3]
	v_cndmask_b32_e64 v200, v226, v200, s[10:11]
	v_cndmask_b32_e64 v201, v226, v201, s[42:43]
	v_fma_f32 v176, s72, v220, v218
	v_fma_f32 v177, s73, v220, v218
	v_fma_f32 v178, s76, v220, v218
	v_fma_f32 v179, s77, v220, v218
	v_fma_f32 v204, v186, |v176|, v74
	v_fma_f32 v205, v186, |v177|, v75
	v_fma_f32 v208, v186, |v178|, v76
	v_fma_f32 v209, v186, |v179|, v77
	v_cmp_le_f32_e64 vcc, |v176|, v171
	v_cmp_le_f32_e64 s[2:3], |v177|, v171
	v_cmp_le_f32_e64 s[10:11], |v178|, v171
	v_cmp_le_f32_e64 s[42:43], |v179|, v171
	v_cndmask_b32_e32 v204, v226, v204, vcc
	v_cndmask_b32_e64 v205, v226, v205, s[2:3]
	v_cndmask_b32_e64 v208, v226, v208, s[10:11]
	v_cndmask_b32_e64 v209, v226, v209, s[42:43]
	v_fma_f32 v176, s80, v220, v218
	v_fma_f32 v177, s81, v220, v218
	v_fma_f32 v212, v186, |v176|, v78
	v_fma_f32 v213, v186, |v177|, v79
	v_fma_f32 v216, v186, |v247|, v80
	v_fma_f32 v217, v186, |v245|, v81
	v_cmp_le_f32_e64 vcc, |v176|, v171
	v_cmp_le_f32_e64 s[2:3], |v177|, v171
	v_cmp_le_f32_e64 s[10:11], |v247|, v171
	v_cmp_le_f32_e64 s[42:43], |v245|, v171
	v_cndmask_b32_e32 v212, v226, v212, vcc
	v_cndmask_b32_e64 v213, v226, v213, s[2:3]
	v_cndmask_b32_e64 v216, v226, v216, s[10:11]
	v_cndmask_b32_e64 v217, v226, v217, s[42:43]

; #define LAS __attribute__((address_space(3)))
; __device__ __forceinline__ unsigned cvtpk(float lo, float hi) { f32x2 v = {lo, hi}; bf16x2_t b = __builtin_convertvector(v, bf16x2_t); return __builtin_bit_cast(unsigned, b); }
; __device__ __forceinline__ s16x4 vtr(LAS const unsigned char* p) { return __builtin_bit_cast(s16x4, __builtin_amdgcn_ds_read_tr16_b64_v4i16((LAS s16x4*)p)); }
; __device__ __forceinline__ void pv(f32x16 (&o)[2], LAS const unsigned char* vp, const bf16x8 (&pa)[4]) {
;     asm volatile("" : "+v"(vp));
; #pragma unroll
;     for (int d0 = 0; d0 < 2; ++d0)
; #pragma unroll
;         for (int ks = 0; ks < 4; ++ks) {
;             const s16x4 lo = vtr(vp + d0 * 4096 + ks * 1024), hh = vtr(vp + d0 * 4096 + ks * 1024 + 512);
;             const bf16x8 vf = (bf16x8){lo[0], lo[1], lo[2], lo[3], hh[0], hh[1], hh[2], hh[3]};
;             o[d0] = __builtin_amdgcn_mfma_f32_32x32x16_bf16(pa[ks], vf, o[d0], 0, 0, 0);
;         }
; template <bool HASNEXT, class Mod>
; __device__ __forceinline__ void softmax2(f32x16& p0, f32x16& p1, f32x16 (&o)[2], f32x16& negm, float& mref, float& l, LAS float* wsf, int lane, const Mod& mod, bf16x8 (&pa)[4], f32x16& n0, f32x16& n1) {
;     ...
;     float s = 0.f;
; #pragma unroll
;     for (int r = 0; r < 16; ++r) { p0[r] = __builtin_amdgcn_exp2f(p0[r]); p1[r] = __builtin_amdgcn_exp2f(p1[r]); s += p0[r] + p1[r]; }
;     l += s;
;     { u32x4 w;
;       w = (u32x4){cvtpk(p0[0], p0[1]), cvtpk(p0[2], p0[3]), cvtpk(p0[4], p0[5]), cvtpk(p0[6], p0[7])}; pa[0] = __builtin_bit_cast(bf16x8, w);
;       w = (u32x4){cvtpk(p0[8], p0[9]), cvtpk(p0[10], p0[11]), cvtpk(p0[12], p0[13]), cvtpk(p0[14], p0[15])}; pa[1] = __builtin_bit_cast(bf16x8, w);
;       w = (u32x4){cvtpk(p1[0], p1[1]), cvtpk(p1[2], p1[3]), cvtpk(p1[4], p1[5]), cvtpk(p1[6], p1[7])}; pa[2] = __builtin_bit_cast(bf16x8, w);
;       w = (u32x4){cvtpk(p1[8], p1[9]), cvtpk(p1[10], p1[11]), cvtpk(p1[12], p1[13]), cvtpk(p1[14], p1[15])}; pa[3] = __builtin_bit_cast(bf16x8, w); }
.Lv50:
	v_mad_i64_i32 v[52:53], s[2:3], v51, s98, v[174:175]
	s_add_i32 s48, s41, 3
	s_lshl_b64 s[2:3], 0xc40, s48
	s_lshl_b64 s[10:11], s[2:3], 1
	v_lshl_add_u64 v[54:55], v[52:53], 0, s[10:11]
	s_lshl_b64 s[42:43], 0x1880, s48
	s_lshl_b64 s[2:3], s[2:3], 2
	global_load_dwordx4 v[130:133], v[52:53], off
	global_load_dwordx4 v[134:137], v[54:55], off
	v_lshl_add_u64 v[56:57], s[42:43], 1, v[52:53]
	v_lshl_add_u64 v[54:55], v[54:55], 0, s[2:3]
	s_lshl_b64 s[42:43], 0x3100, s48
	global_load_dwordx4 v[138:141], v[56:57], off
	global_load_dwordx4 v[142:145], v[54:55], off
	v_lshl_add_u64 v[52:53], s[42:43], 1, v[52:53]
	v_lshl_add_u64 v[54:55], v[54:55], 0, s[2:3]
	global_load_dwordx4 v[146:149], v[52:53], off
	global_load_dwordx4 v[150:153], v[54:55], off
	v_lshl_add_u64 v[52:53], v[54:55], 0, s[10:11]
	global_load_dwordx4 v[154:157], v[52:53], off
	v_lshl_add_u64 v[52:53], v[52:53], 0, s[10:11]
	global_load_dwordx4 v[158:161], v[52:53], off
.LBB0_51:
	ds_read_b64_tr_b16 v[68:69], v243
	ds_read_b64_tr_b16 v[70:71], v243 offset:512
	ds_read_b64_tr_b16 v[72:73], v243 offset:1024
	ds_read_b64_tr_b16 v[74:75], v243 offset:1536
	ds_read_b64_tr_b16 v[76:77], v243 offset:2048
	ds_read_b64_tr_b16 v[78:79], v243 offset:2560
	ds_read_b64_tr_b16 v[250:251], v243 offset:3072
	ds_read_b64_tr_b16 v[252:253], v243 offset:3584
	v_exp_f32_e32 v188, v188
	v_exp_f32_e32 v189, v189
	v_exp_f32_e32 v190, v190
	v_exp_f32_e32 v191, v191
	v_exp_f32_e32 v192, v192
	v_exp_f32_e32 v193, v193
	v_exp_f32_e32 v198, v198
	v_exp_f32_e32 v199, v199
	v_exp_f32_e32 v202, v202
	v_exp_f32_e32 v203, v203
	v_exp_f32_e32 v206, v206
	v_exp_f32_e32 v207, v207
	v_exp_f32_e32 v210, v210
	v_exp_f32_e32 v211, v211
	v_exp_f32_e32 v214, v214
	v_exp_f32_e32 v215, v215
	v_exp_f32_e32 v50, v50
	v_exp_f32_e32 v169, v169
	v_exp_f32_e32 v194, v194
	v_exp_f32_e32 v195, v195
	v_exp_f32_e32 v196, v196
	v_exp_f32_e32 v197, v197
	v_exp_f32_e32 v200, v200
	v_exp_f32_e32 v201, v201
	v_exp_f32_e32 v204, v204
	v_exp_f32_e32 v205, v205
	v_exp_f32_e32 v208, v208
	v_exp_f32_e32 v209, v209
	v_exp_f32_e32 v212, v212
	v_exp_f32_e32 v213, v213
	v_exp_f32_e32 v216, v216
	v_exp_f32_e32 v217, v217
	v_cvt_pk_bf16_f32 v52, v188, v189
	v_cvt_pk_bf16_f32 v53, v190, v191
	v_cvt_pk_bf16_f32 v54, v192, v193
	v_cvt_pk_bf16_f32 v55, v198, v199
	v_cvt_pk_bf16_f32 v56, v202, v203
	v_cvt_pk_bf16_f32 v57, v206, v207
	v_cvt_pk_bf16_f32 v58, v210, v211
	v_cvt_pk_bf16_f32 v59, v214, v215
	v_cvt_pk_bf16_f32 v60, v50, v169
	v_cvt_pk_bf16_f32 v61, v194, v195
	v_cvt_pk_bf16_f32 v62, v196, v197
	v_cvt_pk_bf16_f32 v63, v200, v201
	v_cvt_pk_bf16_f32 v64, v204, v205
	v_cvt_pk_bf16_f32 v65, v208, v209
	v_cvt_pk_bf16_f32 v66, v212, v213
	v_cvt_pk_bf16_f32 v67, v216, v217
	s_waitcnt lgkmcnt(6)
	v_mfma_f32_32x32x16_bf16 v[18:33], v[52:55], v[68:71], v[18:33]
	ds_read_b64_tr_b16 v[68:69], v243 offset:4096
	ds_read_b64_tr_b16 v[70:71], v243 offset:4608
	s_add_i32 s20, s20, 1
	v_add_f32_e32 v188, v188, v189
	v_add_f32_e32 v190, v190, v191
	v_add_f32_e32 v192, v192, v193
	v_add_f32_e32 v198, v198, v199
	s_waitcnt lgkmcnt(6)
	v_mfma_f32_32x32x16_bf16 v[18:33], v[56:59], v[72:75], v[18:33]
	ds_read_b64_tr_b16 v[72:73], v243 offset:5120
	ds_read_b64_tr_b16 v[74:75], v243 offset:5632
	s_and_b64 vcc, exec, s[50:51]
	v_add_f32_e32 v202, v202, v203
	v_add_f32_e32 v206, v206, v207
	v_add_f32_e32 v210, v210, v211
	v_add_f32_e32 v214, v214, v215
	s_waitcnt lgkmcnt(6)
	v_mfma_f32_32x32x16_bf16 v[18:33], v[60:63], v[76:79], v[18:33]
	ds_read_b64_tr_b16 v[76:77], v243 offset:6144
	ds_read_b64_tr_b16 v[78:79], v243 offset:6656
	v_add_f32_e32 v50, v50, v169
	v_add_f32_e32 v194, v194, v195
	v_add_f32_e32 v196, v196, v197
	v_add_f32_e32 v200, v200, v201
	s_waitcnt lgkmcnt(6)
	v_mfma_f32_32x32x16_bf16 v[18:33], v[64:67], v[250:253], v[18:33]
	ds_read_b64_tr_b16 v[250:251], v243 offset:7168
	ds_read_b64_tr_b16 v[252:253], v243 offset:7680
	v_add_f32_e32 v204, v204, v205
	v_add_f32_e32 v208, v208, v209
	v_add_f32_e32 v212, v212, v213
	v_add_f32_e32 v216, v216, v217
	s_waitcnt lgkmcnt(6)
	v_mfma_f32_32x32x16_bf16 v[2:17], v[52:55], v[68:71], v[2:17]
	v_add_f32_e32 v188, v188, v190
	v_add_f32_e32 v192, v192, v198
	v_add_f32_e32 v202, v202, v206
	v_add_f32_e32 v210, v210, v214
	s_waitcnt lgkmcnt(4)
	v_mfma_f32_32x32x16_bf16 v[2:17], v[56:59], v[72:75], v[2:17]
	v_add_f32_e32 v50, v50, v194
	v_add_f32_e32 v196, v196, v200
	v_add_f32_e32 v204, v204, v208
	v_add_f32_e32 v212, v212, v216
	s_waitcnt lgkmcnt(2)
	v_mfma_f32_32x32x16_bf16 v[2:17], v[60:63], v[76:79], v[2:17]
	v_add_f32_e32 v188, v188, v192
	v_add_f32_e32 v202, v202, v210
	v_add_f32_e32 v50, v50, v196
	v_add_f32_e32 v204, v204, v212
	s_waitcnt lgkmcnt(0)
	v_mfma_f32_32x32x16_bf16 v[2:17], v[64:67], v[250:253], v[2:17]
	v_add_f32_e32 v188, v188, v202
	v_add_f32_e32 v50, v50, v204
	v_add_f32_e32 v188, v188, v50
	v_add_f32_e32 v165, v165, v188
	s_cbranch_vccnz .LBB0_58
	s_mov_b32 s42, s0
	s_mov_b32 s43, s41
	s_branch .LBB0_34
	s_nop 0
	s_nop 0
	s_nop 0
	s_nop 0
	s_nop 0
	s_nop 0
	s_nop 0

; __device__ __forceinline__ unsigned cvtpk(float lo, float hi) { f32x2 v = {lo, hi}; bf16x2_t b = __builtin_convertvector(v, bf16x2_t); return __builtin_bit_cast(unsigned, b); }
;     __device__ __forceinline__ void operator()(const f32x4 (&acc)[2][2][4][2], const Unit& u, int wr, int wc, int fr, int fq, const float (&)[8]) const {
;     ...
;             for (int m = 0; m < 4; ++m) { const int row = row0 + ai * HALF + m * 16; bf16_t* rowp = xb + (size_t)row * DM + col0; float s = 0.f;
;                 u32x4 raw[2];
; #pragma unroll
;                 for (int bj = 0; bj < 2; ++bj) raw[bj] = *(const u32x4*)(rowp + bj * HALF);
; #pragma unroll
;                 for (int bj = 0; bj < 2; ++bj) { const f32x4 a0 = acc[ai][bj][m][0], a1 = acc[ai][bj][m][1]; const u32x4 r = raw[bj];
;                     const float x0 = __builtin_bit_cast(float, r.x << 16) + a0[0], x1 = __builtin_bit_cast(float, r.x & 0xffff0000u) + a0[1];
;                     const float x2 = __builtin_bit_cast(float, r.y << 16) + a0[2], x3 = __builtin_bit_cast(float, r.y & 0xffff0000u) + a0[3];
;                     const float x4 = __builtin_bit_cast(float, r.z << 16) + a1[0], x5 = __builtin_bit_cast(float, r.z & 0xffff0000u) + a1[1];
;                     const float x6 = __builtin_bit_cast(float, r.w << 16) + a1[2], x7 = __builtin_bit_cast(float, r.w & 0xffff0000u) + a1[3];
;                     u32x4 w; w.x = cvtpk(x0, x1); w.y = cvtpk(x2, x3); w.z = cvtpk(x4, x5); w.w = cvtpk(x6, x7);
;                     *(u32x4*)(rowp + bj * HALF) = w;
;                     s += ((x0 * x0 + x1 * x1) + (x2 * x2 + x3 * x3)) + ((x4 * x4 + x5 * x5) + (x6 * x6 + x7 * x7)); }
;                 s += __shfl_xor(s, 16); s += __shfl_xor(s, 32);
.LBB0_188:
	s_nop 0
	v_and_b32_e32 v141, 64, v223
	v_xor_b32_e32 v140, 16, v223
	v_add_u32_e32 v141, 64, v141
	v_cmp_lt_i32_e32 vcc, v140, v141
	v_lshl_add_u32 v144, s4, 8, v146
	v_ashrrev_i32_e32 v145, 31, v144
	v_cndmask_b32_e32 v140, v223, v140, vcc
	v_lshlrev_b32_e32 v184, 2, v140
	v_xor_b32_e32 v140, 32, v223
	v_cmp_lt_i32_e32 vcc, v140, v141
	v_readlane_b32 s10, v255, 29
	v_lshl_or_b32 v142, s5, 8, v148
	v_cndmask_b32_e32 v140, v223, v140, vcc
	v_lshlrev_b32_e32 v218, 2, v140
	v_lshlrev_b64 v[140:141], 11, v[144:145]
	v_readlane_b32 s11, v255, 30
	v_ashrrev_i32_e32 v143, 31, v142
	v_and_b32_e32 v163, 48, v223
	v_lshl_add_u64 v[140:141], s[10:11], 0, v[140:141]
	v_lshl_add_u64 v[140:141], v[142:143], 1, v[140:141]
	v_add_u32_e32 v144, v144, v163
	v_lshl_add_u64 v[220:221], v[144:145], 2, s[28:29]
	global_load_dwordx4 v[238:241], v[140:141], off
	global_load_dwordx4 v[242:245], v[140:141], off offset:256
	s_mov_b64 s[2:3], 0x8000
	v_lshl_add_u64 v[150:151], v[140:141], 0, s[2:3]
	global_load_dwordx4 v[246:249], v[150:151], off
	global_load_dwordx4 v[250:253], v[150:151], off offset:256
	s_mov_b64 s[2:3], 0x10000
	v_lshl_add_u64 v[150:151], v[140:141], 0, s[2:3]
	global_load_dwordx4 v[152:155], v[150:151], off
	global_load_dwordx4 v[156:159], v[150:151], off offset:256
	s_mov_b64 s[2:3], 0x18000
	v_lshl_add_u64 v[150:151], v[140:141], 0, s[2:3]
	global_load_dwordx4 v[142:145], v[150:151], off
	global_load_dwordx4 v[160:163], v[150:151], off offset:256
	s_waitcnt vmcnt(7)
	v_lshlrev_b32_e32 v232, 16, v238
	v_and_b32_e32 v233, 0xffff0000, v238
	v_pk_add_f32 v[126:127], v[126:127], v[232:233]
	v_lshlrev_b32_e32 v232, 16, v239
	v_and_b32_e32 v233, 0xffff0000, v239
	v_pk_add_f32 v[128:129], v[128:129], v[232:233]
	v_lshlrev_b32_e32 v232, 16, v240
	v_and_b32_e32 v233, 0xffff0000, v240
	v_pk_add_f32 v[122:123], v[122:123], v[232:233]
	v_lshlrev_b32_e32 v232, 16, v241
	v_and_b32_e32 v233, 0xffff0000, v241
	v_pk_add_f32 v[124:125], v[124:125], v[232:233]
	v_cvt_pk_bf16_f32 v238, v126, v127
	v_cvt_pk_bf16_f32 v239, v128, v129
	v_cvt_pk_bf16_f32 v240, v122, v123
	v_cvt_pk_bf16_f32 v241, v124, v125
	global_store_dwordx4 v[140:141], v[238:241], off
	v_mul_f32_e32 v126, v126, v126
	v_mul_f32_e32 v127, v127, v127
	v_fmac_f32_e32 v126, v128, v128
	v_fmac_f32_e32 v127, v129, v129
	v_fmac_f32_e32 v126, v122, v122
	v_fmac_f32_e32 v127, v123, v123
	v_fmac_f32_e32 v126, v124, v124
	v_fmac_f32_e32 v127, v125, v125
	s_waitcnt vmcnt(7)
	v_lshlrev_b32_e32 v232, 16, v242
	v_and_b32_e32 v233, 0xffff0000, v242
	v_pk_add_f32 v[118:119], v[118:119], v[232:233]
	v_lshlrev_b32_e32 v232, 16, v243
	v_and_b32_e32 v233, 0xffff0000, v243
	v_pk_add_f32 v[120:121], v[120:121], v[232:233]
	v_lshlrev_b32_e32 v232, 16, v244
	v_and_b32_e32 v233, 0xffff0000, v244
	v_pk_add_f32 v[114:115], v[114:115], v[232:233]
	v_lshlrev_b32_e32 v232, 16, v245
	v_and_b32_e32 v233, 0xffff0000, v245
	v_pk_add_f32 v[116:117], v[116:117], v[232:233]
	v_cvt_pk_bf16_f32 v242, v118, v119
	v_cvt_pk_bf16_f32 v243, v120, v121
	v_cvt_pk_bf16_f32 v244, v114, v115
	v_cvt_pk_bf16_f32 v245, v116, v117
	global_store_dwordx4 v[140:141], v[242:245], off offset:256
	v_fmac_f32_e32 v126, v118, v118
	v_fmac_f32_e32 v127, v119, v119
	v_fmac_f32_e32 v126, v120, v120
	v_fmac_f32_e32 v127, v121, v121
	v_fmac_f32_e32 v126, v114, v114
	v_fmac_f32_e32 v127, v115, v115
	v_fmac_f32_e32 v126, v116, v116
	v_fmac_f32_e32 v127, v117, v117
	v_add_f32_e32 v238, v126, v127
	s_mov_b64 s[2:3], 0x40000
	v_lshl_add_u64 v[150:151], v[140:141], 0, s[2:3]
	global_load_dwordx4 v[114:117], v[150:151], off
	global_load_dwordx4 v[118:121], v[150:151], off offset:256
	s_mov_b64 s[2:3], 0x48000
	v_lshl_add_u64 v[150:151], v[140:141], 0, s[2:3]
	global_load_dwordx4 v[122:125], v[150:151], off
	global_load_dwordx4 v[126:129], v[150:151], off offset:256
	s_mov_b64 s[2:3], 0x8000
	v_lshl_add_u64 v[150:151], v[140:141], 0, s[2:3]
	s_waitcnt vmcnt(11)
	v_lshlrev_b32_e32 v232, 16, v246
	v_and_b32_e32 v233, 0xffff0000, v246
	v_pk_add_f32 v[110:111], v[110:111], v[232:233]
	v_lshlrev_b32_e32 v232, 16, v247
	v_and_b32_e32 v233, 0xffff0000, v247
	v_pk_add_f32 v[112:113], v[112:113], v[232:233]
	v_lshlrev_b32_e32 v232, 16, v248
	v_and_b32_e32 v233, 0xffff0000, v248
	v_pk_add_f32 v[106:107], v[106:107], v[232:233]
	v_lshlrev_b32_e32 v232, 16, v249
	v_and_b32_e32 v233, 0xffff0000, v249
	v_pk_add_f32 v[108:109], v[108:109], v[232:233]
	v_cvt_pk_bf16_f32 v246, v110, v111
	v_cvt_pk_bf16_f32 v247, v112, v113
	v_cvt_pk_bf16_f32 v248, v106, v107
	v_cvt_pk_bf16_f32 v249, v108, v109
	global_store_dwordx4 v[150:151], v[246:249], off
	v_mul_f32_e32 v110, v110, v110
	v_mul_f32_e32 v111, v111, v111
	v_fmac_f32_e32 v110, v112, v112
	v_fmac_f32_e32 v111, v113, v113
	v_fmac_f32_e32 v110, v106, v106
	v_fmac_f32_e32 v111, v107, v107
	v_fmac_f32_e32 v110, v108, v108
	v_fmac_f32_e32 v111, v109, v109
	s_waitcnt vmcnt(11)
	v_lshlrev_b32_e32 v232, 16, v250
	v_and_b32_e32 v233, 0xffff0000, v250
	v_pk_add_f32 v[102:103], v[102:103], v[232:233]
	v_lshlrev_b32_e32 v232, 16, v251
	v_and_b32_e32 v233, 0xffff0000, v251
	v_pk_add_f32 v[104:105], v[104:105], v[232:233]
	v_lshlrev_b32_e32 v232, 16, v252
	v_and_b32_e32 v233, 0xffff0000, v252
	v_pk_add_f32 v[98:99], v[98:99], v[232:233]
	v_lshlrev_b32_e32 v232, 16, v253
	v_and_b32_e32 v233, 0xffff0000, v253
	v_pk_add_f32 v[100:101], v[100:101], v[232:233]
	v_cvt_pk_bf16_f32 v250, v102, v103
	v_cvt_pk_bf16_f32 v251, v104, v105
	v_cvt_pk_bf16_f32 v252, v98, v99
	v_cvt_pk_bf16_f32 v253, v100, v101
	global_store_dwordx4 v[150:151], v[250:253], off offset:256
	v_fmac_f32_e32 v110, v102, v102
	v_fmac_f32_e32 v111, v103, v103
	v_fmac_f32_e32 v110, v104, v104
	v_fmac_f32_e32 v111, v105, v105
	v_fmac_f32_e32 v110, v98, v98
	v_fmac_f32_e32 v111, v99, v99
	v_fmac_f32_e32 v110, v100, v100
	v_fmac_f32_e32 v111, v101, v101
	v_add_f32_e32 v246, v110, v111
	s_mov_b64 s[2:3], 0x50000
	v_lshl_add_u64 v[150:151], v[140:141], 0, s[2:3]
	global_load_dwordx4 v[98:101], v[150:151], off
	global_load_dwordx4 v[102:105], v[150:151], off offset:256
	s_mov_b64 s[2:3], 0x58000
	v_lshl_add_u64 v[150:151], v[140:141], 0, s[2:3]
	global_load_dwordx4 v[106:109], v[150:151], off
	global_load_dwordx4 v[110:113], v[150:151], off offset:256
	s_mov_b64 s[2:3], 0x10000
	v_lshl_add_u64 v[150:151], v[140:141], 0, s[2:3]
	s_waitcnt vmcnt(15)
; __device__ __forceinline__ unsigned cvtpk(float lo, float hi) { f32x2 v = {lo, hi}; bf16x2_t b = __builtin_convertvector(v, bf16x2_t); return __builtin_bit_cast(unsigned, b); }
;     __device__ __forceinline__ void operator()(const f32x4 (&acc)[2][2][4][2], const Unit& u, int wr, int wc, int fr, int fq, const float (&)[8]) const {
;     ...
;                 for (int bj = 0; bj < 2; ++bj) { const f32x4 a0 = acc[ai][bj][m][0], a1 = acc[ai][bj][m][1]; const u32x4 r = raw[bj];
;                     const float x0 = __builtin_bit_cast(float, r.x << 16) + a0[0], x1 = __builtin_bit_cast(float, r.x & 0xffff0000u) + a0[1];
;                     const float x2 = __builtin_bit_cast(float, r.y << 16) + a0[2], x3 = __builtin_bit_cast(float, r.y & 0xffff0000u) + a0[3];
;                     const float x4 = __builtin_bit_cast(float, r.z << 16) + a1[0], x5 = __builtin_bit_cast(float, r.z & 0xffff0000u) + a1[1];
;                     const float x6 = __builtin_bit_cast(float, r.w << 16) + a1[2], x7 = __builtin_bit_cast(float, r.w & 0xffff0000u) + a1[3];
;                     u32x4 w; w.x = cvtpk(x0, x1); w.y = cvtpk(x2, x3); w.z = cvtpk(x4, x5); w.w = cvtpk(x6, x7);
;                     *(u32x4*)(rowp + bj * HALF) = w;
;                     s += ((x0 * x0 + x1 * x1) + (x2 * x2 + x3 * x3)) + ((x4 * x4 + x5 * x5) + (x6 * x6 + x7 * x7)); }
;                 s += __shfl_xor(s, 16); s += __shfl_xor(s, 32);
;                 if (fq == 0) atomicAdd(ssq + row, s); }
	v_lshlrev_b32_e32 v232, 16, v152
	v_and_b32_e32 v233, 0xffff0000, v152
	v_pk_add_f32 v[94:95], v[94:95], v[232:233]
	v_lshlrev_b32_e32 v232, 16, v153
	v_and_b32_e32 v233, 0xffff0000, v153
	v_pk_add_f32 v[96:97], v[96:97], v[232:233]
	v_lshlrev_b32_e32 v232, 16, v154
	v_and_b32_e32 v233, 0xffff0000, v154
	v_pk_add_f32 v[90:91], v[90:91], v[232:233]
	v_lshlrev_b32_e32 v232, 16, v155
	v_and_b32_e32 v233, 0xffff0000, v155
	v_pk_add_f32 v[92:93], v[92:93], v[232:233]
	v_cvt_pk_bf16_f32 v152, v94, v95
	v_cvt_pk_bf16_f32 v153, v96, v97
	v_cvt_pk_bf16_f32 v154, v90, v91
	v_cvt_pk_bf16_f32 v155, v92, v93
	global_store_dwordx4 v[150:151], v[152:155], off
	v_mul_f32_e32 v94, v94, v94
	v_mul_f32_e32 v95, v95, v95
	v_fmac_f32_e32 v94, v96, v96
	v_fmac_f32_e32 v95, v97, v97
	v_fmac_f32_e32 v94, v90, v90
	v_fmac_f32_e32 v95, v91, v91
	v_fmac_f32_e32 v94, v92, v92
	v_fmac_f32_e32 v95, v93, v93
	s_waitcnt vmcnt(15)
	v_lshlrev_b32_e32 v232, 16, v156
	v_and_b32_e32 v233, 0xffff0000, v156
	v_pk_add_f32 v[86:87], v[86:87], v[232:233]
	v_lshlrev_b32_e32 v232, 16, v157
	v_and_b32_e32 v233, 0xffff0000, v157
	v_pk_add_f32 v[88:89], v[88:89], v[232:233]
	v_lshlrev_b32_e32 v232, 16, v158
	v_and_b32_e32 v233, 0xffff0000, v158
	v_pk_add_f32 v[82:83], v[82:83], v[232:233]
	v_lshlrev_b32_e32 v232, 16, v159
	v_and_b32_e32 v233, 0xffff0000, v159
	v_pk_add_f32 v[84:85], v[84:85], v[232:233]
	v_cvt_pk_bf16_f32 v156, v86, v87
	v_cvt_pk_bf16_f32 v157, v88, v89
	v_cvt_pk_bf16_f32 v158, v82, v83
	v_cvt_pk_bf16_f32 v159, v84, v85
	global_store_dwordx4 v[150:151], v[156:159], off offset:256
	v_fmac_f32_e32 v94, v86, v86
	v_fmac_f32_e32 v95, v87, v87
	v_fmac_f32_e32 v94, v88, v88
	v_fmac_f32_e32 v95, v89, v89
	v_fmac_f32_e32 v94, v82, v82
	v_fmac_f32_e32 v95, v83, v83
	v_fmac_f32_e32 v94, v84, v84
	v_fmac_f32_e32 v95, v85, v85
	v_add_f32_e32 v229, v94, v95
	s_mov_b64 s[2:3], 0x18000
	v_lshl_add_u64 v[150:151], v[140:141], 0, s[2:3]
	s_waitcnt vmcnt(15)
	v_lshlrev_b32_e32 v232, 16, v142
	v_and_b32_e32 v233, 0xffff0000, v142
	v_pk_add_f32 v[78:79], v[78:79], v[232:233]
	v_lshlrev_b32_e32 v232, 16, v143
	v_and_b32_e32 v233, 0xffff0000, v143
	v_pk_add_f32 v[80:81], v[80:81], v[232:233]
	v_lshlrev_b32_e32 v232, 16, v144
	v_and_b32_e32 v233, 0xffff0000, v144
	v_pk_add_f32 v[74:75], v[74:75], v[232:233]
	v_lshlrev_b32_e32 v232, 16, v145
	v_and_b32_e32 v233, 0xffff0000, v145
	v_pk_add_f32 v[76:77], v[76:77], v[232:233]
	v_cvt_pk_bf16_f32 v142, v78, v79
	v_cvt_pk_bf16_f32 v143, v80, v81
	v_cvt_pk_bf16_f32 v144, v74, v75
	v_cvt_pk_bf16_f32 v145, v76, v77
	global_store_dwordx4 v[150:151], v[142:145], off
	v_mul_f32_e32 v78, v78, v78
	v_mul_f32_e32 v79, v79, v79
	v_fmac_f32_e32 v78, v80, v80
	v_fmac_f32_e32 v79, v81, v81
	v_fmac_f32_e32 v78, v74, v74
	v_fmac_f32_e32 v79, v75, v75
	v_fmac_f32_e32 v78, v76, v76
	v_fmac_f32_e32 v79, v77, v77
	s_waitcnt vmcnt(15)
	v_lshlrev_b32_e32 v232, 16, v160
	v_and_b32_e32 v233, 0xffff0000, v160
	v_pk_add_f32 v[70:71], v[70:71], v[232:233]
	v_lshlrev_b32_e32 v232, 16, v161
	v_and_b32_e32 v233, 0xffff0000, v161
	v_pk_add_f32 v[72:73], v[72:73], v[232:233]
	v_lshlrev_b32_e32 v232, 16, v162
	v_and_b32_e32 v233, 0xffff0000, v162
	v_pk_add_f32 v[66:67], v[66:67], v[232:233]
	v_lshlrev_b32_e32 v232, 16, v163
	v_and_b32_e32 v233, 0xffff0000, v163
	v_pk_add_f32 v[68:69], v[68:69], v[232:233]
	v_cvt_pk_bf16_f32 v160, v70, v71
	v_cvt_pk_bf16_f32 v161, v72, v73
	v_cvt_pk_bf16_f32 v162, v66, v67
	v_cvt_pk_bf16_f32 v163, v68, v69
	global_store_dwordx4 v[150:151], v[160:163], off offset:256
	v_fmac_f32_e32 v78, v70, v70
	v_fmac_f32_e32 v79, v71, v71
	v_fmac_f32_e32 v78, v72, v72
	v_fmac_f32_e32 v79, v73, v73
	v_fmac_f32_e32 v78, v66, v66
	v_fmac_f32_e32 v79, v67, v67
	v_fmac_f32_e32 v78, v68, v68
	v_fmac_f32_e32 v79, v69, v69
	v_add_f32_e32 v232, v78, v79
	v_and_b32_e32 v144, 16, v223
	v_cmp_ne_u32_e32 vcc, 0, v144
	v_and_b32_e32 v144, 32, v223
	s_nop 0
	v_cndmask_b32_e32 v150, v238, v246, vcc
	v_cndmask_b32_e32 v151, v246, v238, vcc
	v_cndmask_b32_e32 v233, v229, v232, vcc
	v_cndmask_b32_e32 v229, v232, v229, vcc
	ds_bpermute_b32 v151, v184, v151
	ds_bpermute_b32 v229, v184, v229
	v_cmp_ne_u32_e32 vcc, 0, v144
	s_waitcnt lgkmcnt(0)
	v_add_f32_e32 v150, v150, v151
	v_add_f32_e32 v233, v233, v229
	v_cndmask_b32_e32 v151, v150, v233, vcc
	v_cndmask_b32_e32 v229, v233, v150, vcc
	ds_bpermute_b32 v229, v218, v229
	s_waitcnt lgkmcnt(0)
	v_add_f32_e32 v151, v151, v229
	global_atomic_add_f32 v[220:221], v151, off
	s_mov_b64 s[2:3], 0x40000
	v_lshl_add_u64 v[150:151], v[140:141], 0, s[2:3]
	s_waitcnt vmcnt(14)
	v_lshlrev_b32_e32 v232, 16, v114
	v_and_b32_e32 v233, 0xffff0000, v114
	v_pk_add_f32 v[62:63], v[62:63], v[232:233]
	v_lshlrev_b32_e32 v232, 16, v115
	v_and_b32_e32 v233, 0xffff0000, v115
	v_pk_add_f32 v[64:65], v[64:65], v[232:233]
	v_lshlrev_b32_e32 v232, 16, v116
	v_and_b32_e32 v233, 0xffff0000, v116
	v_pk_add_f32 v[58:59], v[58:59], v[232:233]
	v_lshlrev_b32_e32 v232, 16, v117
	v_and_b32_e32 v233, 0xffff0000, v117
	v_pk_add_f32 v[60:61], v[60:61], v[232:233]
	v_cvt_pk_bf16_f32 v114, v62, v63
	v_cvt_pk_bf16_f32 v115, v64, v65
	v_cvt_pk_bf16_f32 v116, v58, v59
	v_cvt_pk_bf16_f32 v117, v60, v61
	global_store_dwordx4 v[150:151], v[114:117], off
	v_mul_f32_e32 v62, v62, v62
	v_mul_f32_e32 v63, v63, v63
	v_fmac_f32_e32 v62, v64, v64
	v_fmac_f32_e32 v63, v65, v65
	v_fmac_f32_e32 v62, v58, v58
	v_fmac_f32_e32 v63, v59, v59
	v_fmac_f32_e32 v62, v60, v60
	v_fmac_f32_e32 v63, v61, v61
	s_waitcnt vmcnt(14)
; __device__ __forceinline__ unsigned cvtpk(float lo, float hi) { f32x2 v = {lo, hi}; bf16x2_t b = __builtin_convertvector(v, bf16x2_t); return __builtin_bit_cast(unsigned, b); }
;     __device__ __forceinline__ void operator()(const f32x4 (&acc)[2][2][4][2], const Unit& u, int wr, int wc, int fr, int fq, const float (&)[8]) const {
;     ...
;                 for (int bj = 0; bj < 2; ++bj) { const f32x4 a0 = acc[ai][bj][m][0], a1 = acc[ai][bj][m][1]; const u32x4 r = raw[bj];
;                     const float x0 = __builtin_bit_cast(float, r.x << 16) + a0[0], x1 = __builtin_bit_cast(float, r.x & 0xffff0000u) + a0[1];
;                     const float x2 = __builtin_bit_cast(float, r.y << 16) + a0[2], x3 = __builtin_bit_cast(float, r.y & 0xffff0000u) + a0[3];
;                     const float x4 = __builtin_bit_cast(float, r.z << 16) + a1[0], x5 = __builtin_bit_cast(float, r.z & 0xffff0000u) + a1[1];
;                     const float x6 = __builtin_bit_cast(float, r.w << 16) + a1[2], x7 = __builtin_bit_cast(float, r.w & 0xffff0000u) + a1[3];
;                     u32x4 w; w.x = cvtpk(x0, x1); w.y = cvtpk(x2, x3); w.z = cvtpk(x4, x5); w.w = cvtpk(x6, x7);
;                     *(u32x4*)(rowp + bj * HALF) = w;
;                     s += ((x0 * x0 + x1 * x1) + (x2 * x2 + x3 * x3)) + ((x4 * x4 + x5 * x5) + (x6 * x6 + x7 * x7)); }
	v_lshlrev_b32_e32 v232, 16, v118
	v_and_b32_e32 v233, 0xffff0000, v118
	v_pk_add_f32 v[54:55], v[54:55], v[232:233]
	v_lshlrev_b32_e32 v232, 16, v119
	v_and_b32_e32 v233, 0xffff0000, v119
	v_pk_add_f32 v[56:57], v[56:57], v[232:233]
	v_lshlrev_b32_e32 v232, 16, v120
	v_and_b32_e32 v233, 0xffff0000, v120
	v_pk_add_f32 v[50:51], v[50:51], v[232:233]
	v_lshlrev_b32_e32 v232, 16, v121
	v_and_b32_e32 v233, 0xffff0000, v121
	v_pk_add_f32 v[52:53], v[52:53], v[232:233]
	v_cvt_pk_bf16_f32 v118, v54, v55
	v_cvt_pk_bf16_f32 v119, v56, v57
	v_cvt_pk_bf16_f32 v120, v50, v51
	v_cvt_pk_bf16_f32 v121, v52, v53
	global_store_dwordx4 v[150:151], v[118:121], off offset:256
	v_fmac_f32_e32 v62, v54, v54
	v_fmac_f32_e32 v63, v55, v55
	v_fmac_f32_e32 v62, v56, v56
	v_fmac_f32_e32 v63, v57, v57
	v_fmac_f32_e32 v62, v50, v50
	v_fmac_f32_e32 v63, v51, v51
	v_fmac_f32_e32 v62, v52, v52
	v_fmac_f32_e32 v63, v53, v53
	v_add_f32_e32 v238, v62, v63
	s_mov_b64 s[2:3], 0x48000
	v_lshl_add_u64 v[150:151], v[140:141], 0, s[2:3]
	s_waitcnt vmcnt(14)
	v_lshlrev_b32_e32 v232, 16, v122
	v_and_b32_e32 v233, 0xffff0000, v122
	v_pk_add_f32 v[46:47], v[46:47], v[232:233]
	v_lshlrev_b32_e32 v232, 16, v123
	v_and_b32_e32 v233, 0xffff0000, v123
	v_pk_add_f32 v[48:49], v[48:49], v[232:233]
	v_lshlrev_b32_e32 v232, 16, v124
	v_and_b32_e32 v233, 0xffff0000, v124
	v_pk_add_f32 v[42:43], v[42:43], v[232:233]
	v_lshlrev_b32_e32 v232, 16, v125
	v_and_b32_e32 v233, 0xffff0000, v125
	v_pk_add_f32 v[44:45], v[44:45], v[232:233]
	v_cvt_pk_bf16_f32 v122, v46, v47
	v_cvt_pk_bf16_f32 v123, v48, v49
	v_cvt_pk_bf16_f32 v124, v42, v43
	v_cvt_pk_bf16_f32 v125, v44, v45
	global_store_dwordx4 v[150:151], v[122:125], off
	v_mul_f32_e32 v46, v46, v46
	v_mul_f32_e32 v47, v47, v47
	v_fmac_f32_e32 v46, v48, v48
	v_fmac_f32_e32 v47, v49, v49
	v_fmac_f32_e32 v46, v42, v42
	v_fmac_f32_e32 v47, v43, v43
	v_fmac_f32_e32 v46, v44, v44
	v_fmac_f32_e32 v47, v45, v45
	s_waitcnt vmcnt(14)
	v_lshlrev_b32_e32 v232, 16, v126
	v_and_b32_e32 v233, 0xffff0000, v126
	v_pk_add_f32 v[38:39], v[38:39], v[232:233]
	v_lshlrev_b32_e32 v232, 16, v127
	v_and_b32_e32 v233, 0xffff0000, v127
	v_pk_add_f32 v[40:41], v[40:41], v[232:233]
	v_lshlrev_b32_e32 v232, 16, v128
	v_and_b32_e32 v233, 0xffff0000, v128
	v_pk_add_f32 v[34:35], v[34:35], v[232:233]
	v_lshlrev_b32_e32 v232, 16, v129
	v_and_b32_e32 v233, 0xffff0000, v129
	v_pk_add_f32 v[36:37], v[36:37], v[232:233]
	v_cvt_pk_bf16_f32 v126, v38, v39
	v_cvt_pk_bf16_f32 v127, v40, v41
	v_cvt_pk_bf16_f32 v128, v34, v35
	v_cvt_pk_bf16_f32 v129, v36, v37
	global_store_dwordx4 v[150:151], v[126:129], off offset:256
	v_fmac_f32_e32 v46, v38, v38
	v_fmac_f32_e32 v47, v39, v39
	v_fmac_f32_e32 v46, v40, v40
	v_fmac_f32_e32 v47, v41, v41
	v_fmac_f32_e32 v46, v34, v34
	v_fmac_f32_e32 v47, v35, v35
	v_fmac_f32_e32 v46, v36, v36
	v_fmac_f32_e32 v47, v37, v37
	v_add_f32_e32 v246, v46, v47
	s_mov_b64 s[2:3], 0x50000
	v_lshl_add_u64 v[150:151], v[140:141], 0, s[2:3]
	s_waitcnt vmcnt(12)
	v_lshlrev_b32_e32 v232, 16, v98
	v_and_b32_e32 v233, 0xffff0000, v98
	v_pk_add_f32 v[30:31], v[30:31], v[232:233]
	v_lshlrev_b32_e32 v232, 16, v99
	v_and_b32_e32 v233, 0xffff0000, v99
	v_pk_add_f32 v[32:33], v[32:33], v[232:233]
	v_lshlrev_b32_e32 v232, 16, v100
	v_and_b32_e32 v233, 0xffff0000, v100
	v_pk_add_f32 v[26:27], v[26:27], v[232:233]
	v_lshlrev_b32_e32 v232, 16, v101
	v_and_b32_e32 v233, 0xffff0000, v101
	v_pk_add_f32 v[28:29], v[28:29], v[232:233]
	v_cvt_pk_bf16_f32 v98, v30, v31
	v_cvt_pk_bf16_f32 v99, v32, v33
	v_cvt_pk_bf16_f32 v100, v26, v27
	v_cvt_pk_bf16_f32 v101, v28, v29
	global_store_dwordx4 v[150:151], v[98:101], off
	v_mul_f32_e32 v30, v30, v30
	v_mul_f32_e32 v31, v31, v31
	v_fmac_f32_e32 v30, v32, v32
	v_fmac_f32_e32 v31, v33, v33
	v_fmac_f32_e32 v30, v26, v26
	v_fmac_f32_e32 v31, v27, v27
	v_fmac_f32_e32 v30, v28, v28
	v_fmac_f32_e32 v31, v29, v29
	s_waitcnt vmcnt(12)
; __device__ __forceinline__ unsigned cvtpk(float lo, float hi) { f32x2 v = {lo, hi}; bf16x2_t b = __builtin_convertvector(v, bf16x2_t); return __builtin_bit_cast(unsigned, b); }
;     __device__ __forceinline__ void operator()(const f32x4 (&acc)[2][2][4][2], const Unit& u, int wr, int wc, int fr, int fq, const float (&)[8]) const {
;     ...
;                 for (int bj = 0; bj < 2; ++bj) { const f32x4 a0 = acc[ai][bj][m][0], a1 = acc[ai][bj][m][1]; const u32x4 r = raw[bj];
;                     const float x0 = __builtin_bit_cast(float, r.x << 16) + a0[0], x1 = __builtin_bit_cast(float, r.x & 0xffff0000u) + a0[1];
;                     const float x2 = __builtin_bit_cast(float, r.y << 16) + a0[2], x3 = __builtin_bit_cast(float, r.y & 0xffff0000u) + a0[3];
;                     const float x4 = __builtin_bit_cast(float, r.z << 16) + a1[0], x5 = __builtin_bit_cast(float, r.z & 0xffff0000u) + a1[1];
;                     const float x6 = __builtin_bit_cast(float, r.w << 16) + a1[2], x7 = __builtin_bit_cast(float, r.w & 0xffff0000u) + a1[3];
;                     u32x4 w; w.x = cvtpk(x0, x1); w.y = cvtpk(x2, x3); w.z = cvtpk(x4, x5); w.w = cvtpk(x6, x7);
;                     *(u32x4*)(rowp + bj * HALF) = w;
;                     s += ((x0 * x0 + x1 * x1) + (x2 * x2 + x3 * x3)) + ((x4 * x4 + x5 * x5) + (x6 * x6 + x7 * x7)); }
;                 s += __shfl_xor(s, 16); s += __shfl_xor(s, 32);
;                 if (fq == 0) atomicAdd(ssq + row, s); }
	v_lshlrev_b32_e32 v232, 16, v102
	v_and_b32_e32 v233, 0xffff0000, v102
	v_pk_add_f32 v[22:23], v[22:23], v[232:233]
	v_lshlrev_b32_e32 v232, 16, v103
	v_and_b32_e32 v233, 0xffff0000, v103
	v_pk_add_f32 v[24:25], v[24:25], v[232:233]
	v_lshlrev_b32_e32 v232, 16, v104
	v_and_b32_e32 v233, 0xffff0000, v104
	v_pk_add_f32 v[18:19], v[18:19], v[232:233]
	v_lshlrev_b32_e32 v232, 16, v105
	v_and_b32_e32 v233, 0xffff0000, v105
	v_pk_add_f32 v[20:21], v[20:21], v[232:233]
	v_cvt_pk_bf16_f32 v102, v22, v23
	v_cvt_pk_bf16_f32 v103, v24, v25
	v_cvt_pk_bf16_f32 v104, v18, v19
	v_cvt_pk_bf16_f32 v105, v20, v21
	global_store_dwordx4 v[150:151], v[102:105], off offset:256
	v_fmac_f32_e32 v30, v22, v22
	v_fmac_f32_e32 v31, v23, v23
	v_fmac_f32_e32 v30, v24, v24
	v_fmac_f32_e32 v31, v25, v25
	v_fmac_f32_e32 v30, v18, v18
	v_fmac_f32_e32 v31, v19, v19
	v_fmac_f32_e32 v30, v20, v20
	v_fmac_f32_e32 v31, v21, v21
	v_add_f32_e32 v229, v30, v31
	s_mov_b64 s[2:3], 0x58000
	v_lshl_add_u64 v[150:151], v[140:141], 0, s[2:3]
	s_waitcnt vmcnt(12)
	v_lshlrev_b32_e32 v232, 16, v106
	v_and_b32_e32 v233, 0xffff0000, v106
	v_pk_add_f32 v[14:15], v[14:15], v[232:233]
	v_lshlrev_b32_e32 v232, 16, v107
	v_and_b32_e32 v233, 0xffff0000, v107
	v_pk_add_f32 v[16:17], v[16:17], v[232:233]
	v_lshlrev_b32_e32 v232, 16, v108
	v_and_b32_e32 v233, 0xffff0000, v108
	v_pk_add_f32 v[10:11], v[10:11], v[232:233]
	v_lshlrev_b32_e32 v232, 16, v109
	v_and_b32_e32 v233, 0xffff0000, v109
	v_pk_add_f32 v[12:13], v[12:13], v[232:233]
	v_cvt_pk_bf16_f32 v106, v14, v15
	v_cvt_pk_bf16_f32 v107, v16, v17
	v_cvt_pk_bf16_f32 v108, v10, v11
	v_cvt_pk_bf16_f32 v109, v12, v13
	global_store_dwordx4 v[150:151], v[106:109], off
	v_mul_f32_e32 v14, v14, v14
	v_mul_f32_e32 v15, v15, v15
	v_fmac_f32_e32 v14, v16, v16
	v_fmac_f32_e32 v15, v17, v17
	v_fmac_f32_e32 v14, v10, v10
	v_fmac_f32_e32 v15, v11, v11
	v_fmac_f32_e32 v14, v12, v12
	v_fmac_f32_e32 v15, v13, v13
	s_waitcnt vmcnt(12)
	v_lshlrev_b32_e32 v232, 16, v110
	v_and_b32_e32 v233, 0xffff0000, v110
	v_pk_add_f32 v[6:7], v[6:7], v[232:233]
	v_lshlrev_b32_e32 v232, 16, v111
	v_and_b32_e32 v233, 0xffff0000, v111
	v_pk_add_f32 v[8:9], v[8:9], v[232:233]
	v_lshlrev_b32_e32 v232, 16, v112
	v_and_b32_e32 v233, 0xffff0000, v112
	v_pk_add_f32 v[2:3], v[2:3], v[232:233]
	v_lshlrev_b32_e32 v232, 16, v113
	v_and_b32_e32 v233, 0xffff0000, v113
	v_pk_add_f32 v[4:5], v[4:5], v[232:233]
	v_cvt_pk_bf16_f32 v110, v6, v7
	v_cvt_pk_bf16_f32 v111, v8, v9
	v_cvt_pk_bf16_f32 v112, v2, v3
	v_cvt_pk_bf16_f32 v113, v4, v5
	global_store_dwordx4 v[150:151], v[110:113], off offset:256
	v_fmac_f32_e32 v14, v6, v6
	v_fmac_f32_e32 v15, v7, v7
	v_fmac_f32_e32 v14, v8, v8
	v_fmac_f32_e32 v15, v9, v9
	v_fmac_f32_e32 v14, v2, v2
	v_fmac_f32_e32 v15, v3, v3
	v_fmac_f32_e32 v14, v4, v4
	v_fmac_f32_e32 v15, v5, v5
	v_add_f32_e32 v232, v14, v15
	v_and_b32_e32 v144, 16, v223
	v_cmp_ne_u32_e32 vcc, 0, v144
	v_and_b32_e32 v144, 32, v223
	s_nop 0
	v_cndmask_b32_e32 v150, v238, v246, vcc
	v_cndmask_b32_e32 v151, v246, v238, vcc
	v_cndmask_b32_e32 v233, v229, v232, vcc
	v_cndmask_b32_e32 v229, v232, v229, vcc
	ds_bpermute_b32 v151, v184, v151
	ds_bpermute_b32 v229, v184, v229
	v_cmp_ne_u32_e32 vcc, 0, v144
	s_waitcnt lgkmcnt(0)
	v_add_f32_e32 v150, v150, v151
	v_add_f32_e32 v233, v233, v229
	v_cndmask_b32_e32 v151, v150, v233, vcc
	v_cndmask_b32_e32 v229, v233, v150, vcc
	ds_bpermute_b32 v229, v218, v229
	s_waitcnt lgkmcnt(0)
	v_add_f32_e32 v151, v151, v229
	global_atomic_add_f32 v[220:221], v151, off offset:512
	s_and_b64 vcc, exec, s[42:43]
	s_mov_b64 s[2:3], -1
	s_cbranch_vccnz .LBB0_173
	s_andn2_b64 vcc, exec, s[26:27]
	s_cbranch_vccnz .LBB0_172
	s_barrier
	s_branch .LBB0_172
.LBB0_207:
	s_nop 0
	s_nop 0
	s_nop 0
	s_nop 0
	s_nop 0
	s_nop 0
	s_mov_b64 s[24:25], 0
	s_mov_b64 s[2:3], 0
	s_and_b64 vcc, exec, s[10:11]
	s_cbranch_vccnz .LBB0_162
	s_branch .LBB0_209
